# replace cooperative-groups grid.sync (per-WG wbl2 + single-word spin) with XCD-hierarchical grid barrier in d_ws counter page; one L2 writeback per XCD
# speedup vs baseline: 1.1932x; 1.1932x over previous
; DI unsigned char* WSP(const Params& P) { size_t z = 0; asm volatile("" : "+s"(z)); return P.ws + z; }
; __global__ void __launch_bounds__(256, LB2) fwd_megakernel(Params P) {
;   cg::grid_group grid = cg::this_grid();
;   __shared__ __attribute__((aligned(16))) float lds[17920];
;   __shared__ int s_item;
;   unsigned* cnt = (unsigned*)(WSP(P) + WS_CNT);
;   const int xcd = (int)(__builtin_amdgcn_s_getreg((3 << 11) | 20) & 0xF) & 7;
;   __shared__ int s_rank;
;   if (threadIdx.x == 0) s_rank = (int)atomicAdd(cnt + 900 + xcd, 1u);
;   __syncthreads();
;   const int xrank = s_rank;
_Z14fwd_megakernel6Params:
	v_mov_b32_e32 v1, 0
	v_mov_b32_e32 v248, 0
	global_load_dword v1, v1, s[0:1] offset:278
	s_load_dwordx2 s[4:5], s[0:1], 0x100
	s_load_dwordx16 s[56:71], s[0:1], 0xc0
	v_writelane_b32 v247, s2, 0
	s_add_u32 s6, s0, 0x108
	s_mov_b64 s[2:3], 0
	s_waitcnt lgkmcnt(0)
	v_writelane_b32 v247, s4, 1
	s_addc_u32 s7, s1, 0
	v_and_b32_e32 v160, 0x3ff, v0
	v_writelane_b32 v247, s5, 2
	s_load_dword s4, s[0:1], 0x108
	s_add_u32 s8, s70, s2
	s_addc_u32 s9, s71, s3
	v_cmp_eq_u32_e32 vcc, 0, v160
	s_waitcnt lgkmcnt(0)
	v_writelane_b32 v247, s4, 3
	s_getreg_b32 s4, hwreg(HW_REG_XCC_ID, 0, 4)
	v_writelane_b32 v247, s6, 4
	s_and_b32 s2, s4, 7
	s_waitcnt vmcnt(0)
	v_readfirstlane_b32 s10, v1
	v_writelane_b32 v247, s7, 5
	v_writelane_b32 v247, s2, 6
	s_and_saveexec_b64 s[2:3], vcc
	s_cbranch_execz .LBB0_4
	s_mov_b64 s[6:7], exec
	v_mbcnt_lo_u32_b32 v1, s6, 0
	v_mbcnt_hi_u32_b32 v1, s7, v1
	v_cmp_eq_u32_e32 vcc, 0, v1
	s_and_saveexec_b64 s[4:5], vcc
	s_cbranch_execz .LBB0_3
	v_readlane_b32 s11, v247, 6
	s_lshl_b32 s11, s11, 2
	s_add_u32 s12, s8, s11
	s_addc_u32 s13, s9, 0
	s_bcnt1_i32_b64 s6, s[6:7]
	v_mov_b32_e32 v2, 0x1d000000
	v_mov_b32_e32 v3, s6
	global_atomic_add v2, v2, v3, s[12:13] offset:3600 sc0

; __global__ void __launch_bounds__(256, LB2) fwd_megakernel(Params P) {
;     ...
;     if (rep + 1 < nrep) grid.sync();
;     }
;     if (ph + 1 < P.ph_hi) grid.sync();
;   }
.LBB0_6:
	buffer_inv sc1
	s_waitcnt vmcnt(0)

; __global__ void __launch_bounds__(256, LB2) fwd_megakernel(Params P) {
;     ...
;     if (rep + 1 < nrep) grid.sync();
;     }
;     if (ph + 1 < P.ph_hi) grid.sync();
.LBB0_775:
	s_waitcnt vmcnt(0) lgkmcnt(0)
	s_barrier
	s_mov_b64 s[0:1], exec
	v_readlane_b32 s2, v246, 15
	v_readlane_b32 s3, v246, 16
	s_and_b64 s[2:3], s[0:1], s[2:3]
	s_mov_b64 exec, s[2:3]
	s_cbranch_execnz .LBB0_776
	s_getpc_b64 s[98:99]

; __global__ void __launch_bounds__(256, LB2) fwd_megakernel(Params P) {
;     ...
;     if (rep + 1 < nrep) grid.sync();
;     }
;     if (ph + 1 < P.ph_hi) grid.sync();
.LBB0_776:
	v_readlane_b32 s2, v247, 56
	v_readlane_b32 s3, v247, 57
	v_readlane_b32 s4, v248, 0
	v_readlane_b32 s5, v248, 1
	v_readlane_b32 s6, v248, 2
	v_readlane_b32 s8, v247, 6
	v_mov_b32_e32 v250, 1
	s_add_i32 s7, s6, 1
	s_cmp_lg_u32 s4, 0
	s_cbranch_scc1 .Lgb_arrive
	s_mov_b64 exec, 0xff
	v_mbcnt_lo_u32_b32 v252, -1, 0
	v_lshlrev_b32_e32 v252, 2, v252
	v_readlane_b32 s9, v247, 3
	s_mov_b32 s98, 0
.Lgb_census:
	global_load_dword v251, v252, s[2:3] offset:3600 sc1
	s_mov_b32 s4, 0
	s_mov_b32 s5, 0
	s_waitcnt vmcnt(0)
	v_readlane_b32 s99, v251, 0
	s_add_u32 s4, s4, s99
	s_cmp_lg_u32 s99, 0
	s_addc_u32 s5, s5, 0
	v_readlane_b32 s99, v251, 1
	s_add_u32 s4, s4, s99
	s_cmp_lg_u32 s99, 0
	s_addc_u32 s5, s5, 0
	v_readlane_b32 s99, v251, 2
	s_add_u32 s4, s4, s99
	s_cmp_lg_u32 s99, 0
	s_addc_u32 s5, s5, 0
	v_readlane_b32 s99, v251, 3
	s_add_u32 s4, s4, s99
	s_cmp_lg_u32 s99, 0
	s_addc_u32 s5, s5, 0
	v_readlane_b32 s99, v251, 4
	s_add_u32 s4, s4, s99
	s_cmp_lg_u32 s99, 0
	s_addc_u32 s5, s5, 0
	v_readlane_b32 s99, v251, 5
	s_add_u32 s4, s4, s99
	s_cmp_lg_u32 s99, 0
	s_addc_u32 s5, s5, 0
	v_readlane_b32 s99, v251, 6
	s_add_u32 s4, s4, s99
	s_cmp_lg_u32 s99, 0
	s_addc_u32 s5, s5, 0
	v_readlane_b32 s99, v251, 7
	s_add_u32 s4, s4, s99
	s_cmp_lg_u32 s99, 0
	s_addc_u32 s5, s5, 0
	s_cmp_eq_u32 s4, s9
	s_cbranch_scc1 .Lgb_census_done
	s_sleep 1
	s_add_u32 s98, s98, 1
	s_cmp_lt_u32 s98, 0x40000
	s_cbranch_scc1 .Lgb_census
.Lgb_census_done:
	s_nop 3
	v_readlane_b32 s4, v251, s8
	s_mov_b64 exec, 1
	s_max_u32 s4, s4, 1
	s_max_u32 s5, s5, 1
	v_writelane_b32 v248, s4, 0
	v_writelane_b32 v248, s5, 1
.Lgb_arrive:
	s_lshl_b32 s8, s8, 7
	v_mov_b32_e32 v249, s8
	global_atomic_add v251, v249, v250, s[2:3] offset:768 sc0
	s_mul_i32 s9, s4, s7
	s_waitcnt vmcnt(0)
	v_readfirstlane_b32 s8, v251
	s_add_i32 s8, s8, 1
	s_cmp_eq_u32 s8, s9
	s_cbranch_scc1 .Lgb_leader
	s_mov_b32 s98, 0
.Lgb_wait_local:
	s_sleep 1
	global_load_dword v251, v249, s[2:3] offset:1792 sc1
	s_waitcnt vmcnt(0)
	v_readfirstlane_b32 s8, v251
	s_cmp_ge_u32 s8, s7
	s_cbranch_scc1 .Lgb_done
	s_add_u32 s98, s98, 1
	s_cmp_lt_u32 s98, 0x40000
	s_cbranch_scc1 .Lgb_wait_local
	s_branch .Lgb_done
.Lgb_leader:
	buffer_wbl2 sc1
	s_waitcnt vmcnt(0)
	global_atomic_add v251, v163, v250, s[2:3] offset:2816 sc0
	s_mul_i32 s9, s5, s7
	s_waitcnt vmcnt(0)
	v_readfirstlane_b32 s8, v251
	s_add_i32 s8, s8, 1
	s_cmp_eq_u32 s8, s9
	s_cbranch_scc1 .Lgb_top_last
	s_mov_b32 s98, 0
.Lgb_wait_top:
	s_sleep 1
	global_load_dword v251, v163, s[2:3] offset:2944 sc1
	s_waitcnt vmcnt(0)
	v_readfirstlane_b32 s8, v251
	s_cmp_ge_u32 s8, s7
	s_cbranch_scc1 .Lgb_release
	s_add_u32 s98, s98, 1
	s_cmp_lt_u32 s98, 0x40000
	s_cbranch_scc1 .Lgb_wait_top
	s_branch .Lgb_release
.Lgb_top_last:
	global_atomic_add v163, v250, s[2:3] offset:2944
.Lgb_release:
	global_atomic_add v249, v250, s[2:3] offset:1792
.Lgb_done:
	v_writelane_b32 v248, s7, 2
	s_getpc_b64 s[98:99]

; __global__ void __launch_bounds__(256, LB2) fwd_megakernel(Params P) {
	.amdhsa_kernel _Z14fwd_megakernel6Params
		.amdhsa_group_segment_fixed_size 71944
		.amdhsa_private_segment_fixed_size 0
		.amdhsa_kernarg_size 520
		.amdhsa_user_sgpr_count 2
		.amdhsa_user_sgpr_dispatch_ptr 0
		.amdhsa_user_sgpr_queue_ptr 0
		.amdhsa_user_sgpr_kernarg_segment_ptr 1
		.amdhsa_user_sgpr_dispatch_id 0
		.amdhsa_user_sgpr_kernarg_preload_length 0
		.amdhsa_user_sgpr_kernarg_preload_offset 0
		.amdhsa_user_sgpr_private_segment_size 0
		.amdhsa_uses_dynamic_stack 0
		.amdhsa_enable_private_segment 0
		.amdhsa_system_sgpr_workgroup_id_x 1
		.amdhsa_system_sgpr_workgroup_id_y 0
		.amdhsa_system_sgpr_workgroup_id_z 0
		.amdhsa_system_sgpr_workgroup_info 0
		.amdhsa_system_vgpr_workitem_id 2
		.amdhsa_next_free_vgpr 256
		.amdhsa_next_free_sgpr 100
		.amdhsa_accum_offset 256
		.amdhsa_reserve_vcc 1
		.amdhsa_float_round_mode_32 0
		.amdhsa_float_round_mode_16_64 0
		.amdhsa_float_denorm_mode_32 3
		.amdhsa_float_denorm_mode_16_64 3
		.amdhsa_dx10_clamp 1
		.amdhsa_ieee_mode 1
		.amdhsa_fp16_overflow 0
		.amdhsa_tg_split 0
		.amdhsa_exception_fp_ieee_invalid_op 0
		.amdhsa_exception_fp_denorm_src 0
		.amdhsa_exception_fp_ieee_div_zero 0
		.amdhsa_exception_fp_ieee_overflow 0
		.amdhsa_exception_fp_ieee_underflow 0
		.amdhsa_exception_fp_ieee_inexact 0
		.amdhsa_exception_int_div_zero 0
	.end_amdhsa_kernel

; __global__ void __launch_bounds__(256, LB2) fwd_megakernel(Params P) {
.Lfunc_end0:
	.size	_Z14fwd_megakernel6Params, .Lfunc_end0-_Z14fwd_megakernel6Params
	.set _Z14fwd_megakernel6Params.num_vgpr, 256
	.set _Z14fwd_megakernel6Params.num_agpr, 0
	.set _Z14fwd_megakernel6Params.numbered_sgpr, 100
	.set _Z14fwd_megakernel6Params.num_named_barrier, 0
	.set _Z14fwd_megakernel6Params.private_seg_size, 0
	.set _Z14fwd_megakernel6Params.uses_vcc, 1
	.set _Z14fwd_megakernel6Params.uses_flat_scratch, 0
	.set _Z14fwd_megakernel6Params.has_dyn_sized_stack, 0
	.set _Z14fwd_megakernel6Params.has_recursion, 0
	.set _Z14fwd_megakernel6Params.has_indirect_call, 0

; __global__ void __launch_bounds__(256, LB2) fwd_megakernel(Params P) {
;   cg::grid_group grid = cg::this_grid();
;   __shared__ __attribute__((aligned(16))) float lds[17920];
amdhsa.kernels:
  - .agpr_count:     0
    .args:
      - .offset:         0
        .size:           264
        .value_kind:     by_value
      - .offset:         264
        .size:           4
        .value_kind:     hidden_block_count_x
      - .offset:         268
        .size:           4
        .value_kind:     hidden_block_count_y
      - .offset:         272
        .size:           4
        .value_kind:     hidden_block_count_z
      - .offset:         276
        .size:           2
        .value_kind:     hidden_group_size_x
      - .offset:         278
        .size:           2
        .value_kind:     hidden_group_size_y
      - .offset:         280
        .size:           2
        .value_kind:     hidden_group_size_z
      - .offset:         282
        .size:           2
        .value_kind:     hidden_remainder_x
      - .offset:         284
        .size:           2
        .value_kind:     hidden_remainder_y
      - .offset:         286
        .size:           2
        .value_kind:     hidden_remainder_z
      - .offset:         304
        .size:           8
        .value_kind:     hidden_global_offset_x
      - .offset:         312
        .size:           8
        .value_kind:     hidden_global_offset_y
      - .offset:         320
        .size:           8
        .value_kind:     hidden_global_offset_z
      - .offset:         328
        .size:           2
        .value_kind:     hidden_grid_dims
      - .offset:         352
        .size:           8
        .value_kind:     hidden_multigrid_sync_arg
    .group_segment_fixed_size: 71944
    .kernarg_segment_align: 8
    .kernarg_segment_size: 520
    .language:       OpenCL C
    .language_version:
      - 2
      - 0
    .max_flat_workgroup_size: 256
    .name:           _Z14fwd_megakernel6Params
    .private_segment_fixed_size: 0
    .sgpr_count:     106
    .sgpr_spill_count: 210
    .symbol:         _Z14fwd_megakernel6Params.kd
    .uniform_work_group_size: 1
    .uses_dynamic_stack: false
    .vgpr_count:     256
    .vgpr_spill_count: 0
    .wavefront_size: 64
